# attnA step A: softmax head of tile J (8 exp, 4 cvt, 8 add) issued inside the QK(J+1) MFMA shadows so the first PV MFMA follows the QK block directly
# speedup vs baseline: 1.0049x; 1.0049x over previous
.LBB0_1369:
	s_or_b32 s82, s34, 1
	s_lshl_b64 s[4:5], s[82:83], 7
	s_add_u32 s4, s8, s4
	s_addc_u32 s5, s9, s5
	s_add_u32 m0, s38, 0x8000
	s_nop 0
	global_load_lds_dwordx4 v198, s[4:5]
	s_add_u32 m0, s38, 0x9000
	s_nop 0
	global_load_lds_dwordx4 v199, s[4:5]
	s_add_u32 m0, s38, 0xa000
	s_nop 0
	global_load_lds_dwordx4 v200, s[4:5]
	s_add_u32 m0, s38, 0xb000
	s_nop 0
	global_load_lds_dwordx4 v201, s[4:5]
	v_cmp_lt_i32_e64 s[4:5], s34, v226
	s_and_saveexec_b64 s[22:23], s[4:5]
	s_cbranch_execz .LBB0_1371
	ds_read_b128 v[2:5], v222 offset:24576
	ds_read_b128 v[6:9], v222 offset:28672
	ds_read_b128 v[10:13], v223 offset:24576
	ds_read_b128 v[244:247], v223 offset:28672
	s_waitcnt lgkmcnt(3)
	v_mfma_f32_32x32x16_bf16 v[128:143], v[2:5], v[160:163], v[16:31]
	v_exp_f32_e32 v32, v32
	v_exp_f32_e32 v33, v33
	ds_read_b128 v[2:5], v224 offset:24576
	s_waitcnt lgkmcnt(3)
	v_mfma_f32_32x32x16_bf16 v[144:159], v[6:9], v[160:163], v[16:31]
	v_exp_f32_e32 v34, v34
	v_exp_f32_e32 v35, v35
	ds_read_b128 v[6:9], v224 offset:28672
	s_waitcnt lgkmcnt(3)
	v_mfma_f32_32x32x16_bf16 v[128:143], v[10:13], v[164:167], v[128:143]
	v_exp_f32_e32 v36, v36
	v_exp_f32_e32 v37, v37
	v_add_f32_e32 v0, 0, v32
	ds_read_b128 v[10:13], v225 offset:24576
	s_waitcnt lgkmcnt(3)
	v_mfma_f32_32x32x16_bf16 v[144:159], v[244:247], v[164:167], v[144:159]
	v_exp_f32_e32 v38, v38
	v_exp_f32_e32 v39, v39
	v_add_f32_e32 v0, v33, v0
	ds_read_b128 v[244:247], v225 offset:28672
	s_waitcnt lgkmcnt(3)
	v_mfma_f32_32x32x16_bf16 v[128:143], v[2:5], v[168:171], v[128:143]
	v_cvt_pk_bf16_f32 v208, v32, v33
	v_add_f32_e32 v0, v34, v0
	v_add_f32_e32 v0, v35, v0
	s_waitcnt lgkmcnt(2)
	v_mfma_f32_32x32x16_bf16 v[144:159], v[6:9], v[168:171], v[144:159]
	v_cvt_pk_bf16_f32 v209, v34, v35
	v_add_f32_e32 v0, v36, v0
	v_add_f32_e32 v0, v37, v0
	s_waitcnt lgkmcnt(1)
	v_mfma_f32_32x32x16_bf16 v[128:143], v[10:13], v[172:175], v[128:143]
	v_cvt_pk_bf16_f32 v210, v36, v37
	v_add_f32_e32 v0, v38, v0
	s_waitcnt lgkmcnt(0)
	v_mfma_f32_32x32x16_bf16 v[144:159], v[244:247], v[172:175], v[144:159]
	v_cvt_pk_bf16_f32 v211, v38, v39
	v_add_f32_e32 v0, v39, v0
	s_or_b64 exec, exec, s[22:23]
	v_cmp_le_i32_e32 vcc, s34, v226
	s_and_saveexec_b64 s[22:23], vcc
	ds_read_b64 v[6:7], v228 offset:8192
	ds_read_b64 v[8:9], v229 offset:8192
	ds_read_b64 v[10:11], v230 offset:20480
	ds_read_b64 v[12:13], v231 offset:20480
	ds_read_b64 v[244:245], v230 offset:12288
	ds_read_b64 v[246:247], v231 offset:12288
	ds_read_b64 v[32:33], v230 offset:16384
	ds_read_b64 v[34:35], v231 offset:16384
	ds_read_b64 v[36:37], v232 offset:8192
	ds_read_b64 v[38:39], v233 offset:8192
	s_waitcnt lgkmcnt(8)
	v_mfma_f32_32x32x16_bf16 v[112:127], v[6:9], v[208:211], v[112:127]
	ds_read_b64 v[6:7], v234 offset:20480
	ds_read_b64 v[8:9], v235 offset:20480
	v_exp_f32_e32 v40, v40
	v_exp_f32_e32 v41, v41
	s_waitcnt lgkmcnt(8)
	v_mfma_f32_32x32x16_bf16 v[64:79], v[10:13], v[208:211], v[64:79]
	ds_read_b64 v[10:11], v234 offset:12288
	ds_read_b64 v[12:13], v235 offset:12288
	v_exp_f32_e32 v42, v42
	v_exp_f32_e32 v43, v43
	v_add_f32_e32 v0, v40, v0
	v_add_f32_e32 v0, v41, v0
	s_waitcnt lgkmcnt(8)
	v_mfma_f32_32x32x16_bf16 v[96:111], v[244:247], v[208:211], v[96:111]
	ds_read_b64 v[244:245], v234 offset:16384
	ds_read_b64 v[246:247], v235 offset:16384
	v_exp_f32_e32 v44, v44
	v_exp_f32_e32 v45, v45
	v_add_f32_e32 v0, v42, v0
	v_add_f32_e32 v0, v43, v0
	s_waitcnt lgkmcnt(8)
	v_mfma_f32_32x32x16_bf16 v[80:95], v[32:35], v[208:211], v[80:95]
	ds_read_b64 v[32:33], v236 offset:8192
	ds_read_b64 v[34:35], v237 offset:8192
	v_exp_f32_e32 v46, v46
	v_exp_f32_e32 v47, v47
	v_add_f32_e32 v0, v44, v0
	v_add_f32_e32 v0, v45, v0
	v_add_f32_e32 v0, v46, v0
	v_add_f32_e32 v0, v47, v0
	v_cvt_pk_bf16_f32 v2, v40, v41
	v_cvt_pk_bf16_f32 v3, v42, v43
	v_cvt_pk_bf16_f32 v4, v44, v45
	v_cvt_pk_bf16_f32 v5, v46, v47
	s_nop 1
	ds_read_b64 v[40:41], v238 offset:20480
	ds_read_b64 v[42:43], v239 offset:20480
	s_waitcnt lgkmcnt(10)
	v_mfma_f32_32x32x16_bf16 v[112:127], v[36:39], v[2:5], v[112:127]
	ds_read_b64 v[44:45], v238 offset:12288
	ds_read_b64 v[46:47], v239 offset:12288
	v_exp_f32_e32 v48, v48
	v_exp_f32_e32 v49, v49
	s_waitcnt lgkmcnt(10)
	v_mfma_f32_32x32x16_bf16 v[64:79], v[6:9], v[2:5], v[64:79]
	ds_read_b64 v[36:37], v238 offset:16384
	ds_read_b64 v[38:39], v239 offset:16384
	v_exp_f32_e32 v50, v50
	v_exp_f32_e32 v51, v51
	v_add_f32_e32 v0, v48, v0
	v_add_f32_e32 v0, v49, v0
	s_waitcnt lgkmcnt(10)
	v_mfma_f32_32x32x16_bf16 v[96:111], v[10:13], v[2:5], v[96:111]
	ds_read_b64 v[6:7], v240 offset:8192
	ds_read_b64 v[8:9], v241 offset:8192
	v_exp_f32_e32 v52, v52
	v_exp_f32_e32 v53, v53
	v_add_f32_e32 v0, v50, v0
	v_add_f32_e32 v0, v51, v0
	s_waitcnt lgkmcnt(10)
	v_mfma_f32_32x32x16_bf16 v[80:95], v[244:247], v[2:5], v[80:95]
	ds_read_b64 v[10:11], v242 offset:12288
	ds_read_b64 v[12:13], v243 offset:12288
	v_exp_f32_e32 v54, v54
	v_exp_f32_e32 v55, v55
	v_add_f32_e32 v0, v52, v0
	v_add_f32_e32 v0, v53, v0
	v_add_f32_e32 v0, v54, v0
	v_add_f32_e32 v0, v55, v0
	v_cvt_pk_bf16_f32 v2, v48, v49
	v_cvt_pk_bf16_f32 v3, v50, v51
	v_cvt_pk_bf16_f32 v4, v52, v53
	v_cvt_pk_bf16_f32 v5, v54, v55
	s_nop 1
	ds_read_b64 v[244:245], v242 offset:16384
	ds_read_b64 v[246:247], v243 offset:16384
	s_waitcnt lgkmcnt(12)
	v_mfma_f32_32x32x16_bf16 v[112:127], v[32:35], v[2:5], v[112:127]
	ds_read_b64 v[48:49], v242 offset:20480
	ds_read_b64 v[50:51], v243 offset:20480
	v_exp_f32_e32 v56, v56
	v_exp_f32_e32 v57, v57
	s_waitcnt lgkmcnt(12)
	v_mfma_f32_32x32x16_bf16 v[64:79], v[40:43], v[2:5], v[64:79]
	v_exp_f32_e32 v58, v58
	v_exp_f32_e32 v59, v59
	v_add_f32_e32 v0, v56, v0
	v_add_f32_e32 v0, v57, v0
	s_waitcnt lgkmcnt(10)
	v_mfma_f32_32x32x16_bf16 v[96:111], v[44:47], v[2:5], v[96:111]
	v_exp_f32_e32 v60, v60
	v_exp_f32_e32 v61, v61
	v_add_f32_e32 v0, v58, v0
	v_add_f32_e32 v0, v59, v0
	s_waitcnt lgkmcnt(8)
	v_mfma_f32_32x32x16_bf16 v[80:95], v[36:39], v[2:5], v[80:95]
	v_exp_f32_e32 v62, v62
	v_exp_f32_e32 v63, v63
	v_add_f32_e32 v0, v60, v0
	v_add_f32_e32 v0, v61, v0
	v_add_f32_e32 v0, v62, v0
	v_add_f32_e32 v0, v63, v0
	v_cvt_pk_bf16_f32 v2, v56, v57
	v_cvt_pk_bf16_f32 v3, v58, v59
	v_cvt_pk_bf16_f32 v4, v60, v61
	v_cvt_pk_bf16_f32 v5, v62, v63
	s_nop 1
	s_waitcnt lgkmcnt(6)
	v_mfma_f32_32x32x16_bf16 v[112:127], v[6:9], v[2:5], v[112:127]
	s_waitcnt lgkmcnt(4)
	v_mfma_f32_32x32x16_bf16 v[96:111], v[10:13], v[2:5], v[96:111]
	s_waitcnt lgkmcnt(2)
	v_mfma_f32_32x32x16_bf16 v[80:95], v[244:247], v[2:5], v[80:95]
	s_waitcnt lgkmcnt(0)
	v_mfma_f32_32x32x16_bf16 v[64:79], v[48:51], v[2:5], v[64:79]
	v_add_f32_e32 v227, v227, v0
	s_branch .LBB0_1373

.LBB0_1411:
	s_or_b32 s82, s31, 1
	s_lshl_b64 s[4:5], s[82:83], 7
	s_add_u32 s4, s8, s4
	s_addc_u32 s5, s9, s5
	s_add_u32 m0, s38, 0x8000
	s_nop 0
	global_load_lds_dwordx4 v196, s[4:5]
	s_add_u32 m0, s38, 0x9000
	s_nop 0
	global_load_lds_dwordx4 v197, s[4:5]
	s_add_u32 m0, s38, 0xa000
	s_nop 0
	global_load_lds_dwordx4 v198, s[4:5]
	s_add_u32 m0, s38, 0xb000
	s_nop 0
	global_load_lds_dwordx4 v199, s[4:5]
	v_cmp_lt_i32_e64 s[4:5], s31, v225
	s_and_saveexec_b64 s[22:23], s[4:5]
	s_cbranch_execz .LBB0_1413
	ds_read_b128 v[2:5], v220 offset:24576
	ds_read_b128 v[6:9], v220 offset:28672
	ds_read_b128 v[10:13], v221 offset:24576
	ds_read_b128 v[244:247], v221 offset:28672
	s_waitcnt lgkmcnt(3)
	v_mfma_f32_32x32x16_bf16 v[128:143], v[2:5], v[160:163], v[16:31]
	v_exp_f32_e32 v80, v80
	v_exp_f32_e32 v81, v81
	ds_read_b128 v[2:5], v222 offset:24576
	s_waitcnt lgkmcnt(3)
	v_mfma_f32_32x32x16_bf16 v[144:159], v[6:9], v[160:163], v[16:31]
	v_exp_f32_e32 v82, v82
	v_exp_f32_e32 v83, v83
	ds_read_b128 v[6:9], v222 offset:28672
	s_waitcnt lgkmcnt(3)
	v_mfma_f32_32x32x16_bf16 v[128:143], v[10:13], v[164:167], v[128:143]
	v_exp_f32_e32 v84, v84
	v_exp_f32_e32 v85, v85
	v_add_f32_e32 v0, 0, v80
	ds_read_b128 v[10:13], v223 offset:24576
	s_waitcnt lgkmcnt(3)
	v_mfma_f32_32x32x16_bf16 v[144:159], v[244:247], v[164:167], v[144:159]
	v_exp_f32_e32 v86, v86
	v_exp_f32_e32 v87, v87
	v_add_f32_e32 v0, v81, v0
	ds_read_b128 v[244:247], v223 offset:28672
	s_waitcnt lgkmcnt(3)
	v_mfma_f32_32x32x16_bf16 v[128:143], v[2:5], v[168:171], v[128:143]
	v_cvt_pk_bf16_f32 v208, v80, v81
	v_add_f32_e32 v0, v82, v0
	v_add_f32_e32 v0, v83, v0
	s_waitcnt lgkmcnt(2)
	v_mfma_f32_32x32x16_bf16 v[144:159], v[6:9], v[168:171], v[144:159]
	v_cvt_pk_bf16_f32 v209, v82, v83
	v_add_f32_e32 v0, v84, v0
	v_add_f32_e32 v0, v85, v0
	s_waitcnt lgkmcnt(1)
	v_mfma_f32_32x32x16_bf16 v[128:143], v[10:13], v[172:175], v[128:143]
	v_cvt_pk_bf16_f32 v210, v84, v85
	v_add_f32_e32 v0, v86, v0
	s_waitcnt lgkmcnt(0)
	v_mfma_f32_32x32x16_bf16 v[144:159], v[244:247], v[172:175], v[144:159]
	v_cvt_pk_bf16_f32 v211, v86, v87
	v_add_f32_e32 v0, v87, v0
	s_or_b64 exec, exec, s[22:23]
	v_cmp_le_i32_e32 vcc, s31, v225
	s_and_saveexec_b64 s[22:23], vcc
	ds_read_b64 v[6:7], v226 offset:8192
	ds_read_b64 v[8:9], v227 offset:8192
	ds_read_b64 v[10:11], v228 offset:20480
	ds_read_b64 v[12:13], v229 offset:20480
	ds_read_b64 v[242:243], v228 offset:12288
	ds_read_b64 v[244:245], v229 offset:12288
	ds_read_b64 v[80:81], v228 offset:16384
	ds_read_b64 v[82:83], v229 offset:16384
	ds_read_b64 v[84:85], v230 offset:8192
	ds_read_b64 v[86:87], v231 offset:8192
	s_waitcnt lgkmcnt(8)
	v_mfma_f32_32x32x16_bf16 v[64:79], v[6:9], v[208:211], v[64:79]
	ds_read_b64 v[6:7], v232 offset:20480
	ds_read_b64 v[8:9], v233 offset:20480
	v_exp_f32_e32 v88, v88
	v_exp_f32_e32 v89, v89
	s_waitcnt lgkmcnt(8)
	v_mfma_f32_32x32x16_bf16 v[112:127], v[10:13], v[208:211], v[112:127]
	ds_read_b64 v[10:11], v232 offset:12288
	ds_read_b64 v[12:13], v233 offset:12288
	v_exp_f32_e32 v90, v90
	v_exp_f32_e32 v91, v91
	v_add_f32_e32 v0, v88, v0
	v_add_f32_e32 v0, v89, v0
	s_waitcnt lgkmcnt(8)
	v_mfma_f32_32x32x16_bf16 v[48:63], v[242:245], v[208:211], v[48:63]
	ds_read_b64 v[242:243], v232 offset:16384
	ds_read_b64 v[244:245], v233 offset:16384
	v_exp_f32_e32 v92, v92
	v_exp_f32_e32 v93, v93
	v_add_f32_e32 v0, v90, v0
	v_add_f32_e32 v0, v91, v0
	s_waitcnt lgkmcnt(8)
	v_mfma_f32_32x32x16_bf16 v[32:47], v[80:83], v[208:211], v[32:47]
	ds_read_b64 v[80:81], v234 offset:8192
	ds_read_b64 v[82:83], v235 offset:8192
	v_exp_f32_e32 v94, v94
	v_exp_f32_e32 v95, v95
	v_add_f32_e32 v0, v92, v0
	v_add_f32_e32 v0, v93, v0
	v_add_f32_e32 v0, v94, v0
	v_add_f32_e32 v0, v95, v0
	v_cvt_pk_bf16_f32 v2, v88, v89
	v_cvt_pk_bf16_f32 v3, v90, v91
	v_cvt_pk_bf16_f32 v4, v92, v93
	v_cvt_pk_bf16_f32 v5, v94, v95
	s_nop 1
	ds_read_b64 v[88:89], v236 offset:20480
	ds_read_b64 v[90:91], v237 offset:20480
	s_waitcnt lgkmcnt(10)
	v_mfma_f32_32x32x16_bf16 v[64:79], v[84:87], v[2:5], v[64:79]
	ds_read_b64 v[92:93], v236 offset:12288
	ds_read_b64 v[94:95], v237 offset:12288
	v_exp_f32_e32 v96, v96
	v_exp_f32_e32 v97, v97
	s_waitcnt lgkmcnt(10)
	v_mfma_f32_32x32x16_bf16 v[112:127], v[6:9], v[2:5], v[112:127]
	ds_read_b64 v[84:85], v236 offset:16384
	ds_read_b64 v[86:87], v237 offset:16384
	v_exp_f32_e32 v98, v98
	v_exp_f32_e32 v99, v99
	v_add_f32_e32 v0, v96, v0
	v_add_f32_e32 v0, v97, v0
	s_waitcnt lgkmcnt(10)
	v_mfma_f32_32x32x16_bf16 v[48:63], v[10:13], v[2:5], v[48:63]
	ds_read_b64 v[6:7], v238 offset:8192
	ds_read_b64 v[8:9], v239 offset:8192
	v_exp_f32_e32 v100, v100
	v_exp_f32_e32 v101, v101
	v_add_f32_e32 v0, v98, v0
	v_add_f32_e32 v0, v99, v0
	s_waitcnt lgkmcnt(10)
	v_mfma_f32_32x32x16_bf16 v[32:47], v[242:245], v[2:5], v[32:47]
	ds_read_b64 v[10:11], v240 offset:12288
	ds_read_b64 v[12:13], v241 offset:12288
	v_exp_f32_e32 v102, v102
	v_exp_f32_e32 v103, v103
	v_add_f32_e32 v0, v100, v0
	v_add_f32_e32 v0, v101, v0
	v_add_f32_e32 v0, v102, v0
	v_add_f32_e32 v0, v103, v0
	v_cvt_pk_bf16_f32 v2, v96, v97
	v_cvt_pk_bf16_f32 v3, v98, v99
	v_cvt_pk_bf16_f32 v4, v100, v101
	v_cvt_pk_bf16_f32 v5, v102, v103
	s_nop 1
	ds_read_b64 v[242:243], v240 offset:16384
	ds_read_b64 v[244:245], v241 offset:16384
	s_waitcnt lgkmcnt(12)
	v_mfma_f32_32x32x16_bf16 v[64:79], v[80:83], v[2:5], v[64:79]
	ds_read_b64 v[96:97], v240 offset:20480
	ds_read_b64 v[98:99], v241 offset:20480
	v_exp_f32_e32 v104, v104
	v_exp_f32_e32 v105, v105
	s_waitcnt lgkmcnt(12)
	v_mfma_f32_32x32x16_bf16 v[112:127], v[88:91], v[2:5], v[112:127]
	v_exp_f32_e32 v106, v106
	v_exp_f32_e32 v107, v107
	v_add_f32_e32 v0, v104, v0
	v_add_f32_e32 v0, v105, v0
	s_waitcnt lgkmcnt(10)
	v_mfma_f32_32x32x16_bf16 v[48:63], v[92:95], v[2:5], v[48:63]
	v_exp_f32_e32 v108, v108
	v_exp_f32_e32 v109, v109
	v_add_f32_e32 v0, v106, v0
	v_add_f32_e32 v0, v107, v0
	s_waitcnt lgkmcnt(8)
	v_mfma_f32_32x32x16_bf16 v[32:47], v[84:87], v[2:5], v[32:47]
	v_exp_f32_e32 v110, v110
	v_exp_f32_e32 v111, v111
	v_add_f32_e32 v0, v108, v0
	v_add_f32_e32 v0, v109, v0
	v_add_f32_e32 v0, v110, v0
	v_add_f32_e32 v0, v111, v0
	v_cvt_pk_bf16_f32 v2, v104, v105
	v_cvt_pk_bf16_f32 v3, v106, v107
	v_cvt_pk_bf16_f32 v4, v108, v109
	v_cvt_pk_bf16_f32 v5, v110, v111
	s_nop 1
	s_waitcnt lgkmcnt(6)
	v_mfma_f32_32x32x16_bf16 v[64:79], v[6:9], v[2:5], v[64:79]
	s_waitcnt lgkmcnt(4)
	v_mfma_f32_32x32x16_bf16 v[48:63], v[10:13], v[2:5], v[48:63]
	s_waitcnt lgkmcnt(2)
	v_mfma_f32_32x32x16_bf16 v[32:47], v[242:245], v[2:5], v[32:47]
	s_waitcnt lgkmcnt(0)
	v_mfma_f32_32x32x16_bf16 v[112:127], v[96:99], v[2:5], v[112:127]
	v_add_f32_e32 v224, v224, v0
	s_branch .LBB0_1415
